# norm-weight loads in the attention epilogue and the SSD chunk-output finalisation are waited for at their first consumer instead of right after issue
# baseline (speedup 1.0000x reference)
.LBB0_1694:
	s_or_b64 exec, exec, s[2:3]
	s_waitcnt lgkmcnt(0)
	s_barrier
	s_load_dwordx2 s[2:3], s[0:1], 0x78
	s_lshl_b64 s[6:7], s[56:57], 2
	v_lshlrev_b32_e32 v0, 2, v187
	v_lshlrev_b32_e32 v136, 1, v187
	s_waitcnt lgkmcnt(0)
	s_add_u32 s2, s2, s6
	s_addc_u32 s3, s3, s7
	global_load_dwordx4 v[28:31], v0, s[2:3]
	global_load_dwordx4 v[24:27], v0, s[2:3] offset:32
	global_load_dwordx4 v[20:23], v0, s[2:3] offset:64
	global_load_dwordx4 v[16:19], v0, s[2:3] offset:96
	global_load_dwordx4 v[12:15], v0, s[2:3] offset:128
	global_load_dwordx4 v[8:11], v0, s[2:3] offset:160
	global_load_dwordx4 v[4:7], v0, s[2:3] offset:192
	s_nop 0
	global_load_dwordx4 v[0:3], v0, s[2:3] offset:224
	s_add_i32 s2, 0, 0x21800
	v_lshl_add_u32 v58, v186, 2, s2
	s_add_i32 s52, s52, s92
	s_cmpk_lt_i32 s52, 0x200
	ds_read2st64_b32 v[56:57], v58 offset1:1
	s_waitcnt lgkmcnt(0)
	v_add_f32_e32 v56, 0, v56
	v_add_f32_e32 v59, v56, v57
	ds_read2st64_b32 v[56:57], v58 offset0:2 offset1:3
	s_waitcnt lgkmcnt(0)
	v_add_f32_e32 v56, v59, v56
	v_add_f32_e32 v59, v56, v57
	ds_read2st64_b32 v[56:57], v58 offset0:4 offset1:5
	s_waitcnt lgkmcnt(0)
	v_add_f32_e32 v56, v59, v56
	v_add_f32_e32 v59, v56, v57
	ds_read2st64_b32 v[56:57], v58 offset0:6 offset1:7
	s_waitcnt lgkmcnt(0)
	v_add_f32_e32 v56, v59, v56
	v_add_f32_e32 v56, v56, v57
	v_fmamk_f32 v56, v56, 0x3b000000, v181
	v_cmp_gt_f32_e32 vcc, s13, v56
	v_mul_f32_e32 v57, 0x4f800000, v56
	s_nop 0
	v_cndmask_b32_e32 v56, v56, v57, vcc
	v_sqrt_f32_e32 v57, v56
	s_nop 0
	v_add_u32_e32 v58, -1, v57
	v_fma_f32 v59, -v58, v57, v56
	v_cmp_ge_f32_e64 s[42:43], 0, v59
	v_add_u32_e32 v59, 1, v57
	s_nop 0
	v_cndmask_b32_e64 v58, v57, v58, s[42:43]
	v_fma_f32 v57, -v59, v57, v56
	v_cmp_lt_f32_e64 s[42:43], 0, v57
	s_nop 1
	v_cndmask_b32_e64 v57, v58, v59, s[42:43]
	v_mul_f32_e32 v58, 0x37800000, v57
	v_cndmask_b32_e32 v57, v57, v58, vcc
	v_cmp_class_f32_e32 vcc, v56, v182
	s_nop 1
	v_cndmask_b32_e32 v56, v57, v56, vcc
	v_div_scale_f32 v57, s[6:7], v56, v56, 1.0
	v_rcp_f32_e32 v58, v57
	s_nop 0
	v_fma_f32 v59, -v57, v58, 1.0
	v_fmac_f32_e32 v58, v59, v58
	v_div_scale_f32 v59, vcc, 1.0, v56, 1.0
	v_mul_f32_e32 v60, v59, v58
	v_fma_f32 v61, -v57, v60, v59
	v_fmac_f32_e32 v60, v61, v58
	v_fma_f32 v57, -v57, v60, v59
	v_div_fmas_f32 v57, v57, v58, v60
	v_lshlrev_b64 v[58:59], 11, v[144:145]
	v_div_fixup_f32 v56, v57, v56, 1.0
	v_lshl_add_u64 v[58:59], s[54:55], 0, v[58:59]
	v_lshl_add_u64 v[58:59], v[58:59], 0, s[4:5]
	v_pk_mul_f32 v[60:61], v[64:65], v[56:57] op_sel_hi:[1,0]
	v_pk_mul_f32 v[62:63], v[66:67], v[56:57] op_sel_hi:[1,0]
	s_waitcnt vmcnt(0)
	v_pk_mul_f32 v[60:61], v[28:29], v[60:61]
	v_pk_mul_f32 v[62:63], v[30:31], v[62:63]
	v_lshl_add_u64 v[58:59], v[58:59], 0, v[136:137]
	v_cvt_pk_bf16_f32 v60, v60, v61
	v_cvt_pk_bf16_f32 v61, v62, v63
	v_lshl_add_u64 v[62:63], v[58:59], 0, s[34:35]
	v_add_co_u32_e32 v58, vcc, s14, v58
	s_nop 1
	v_addc_co_u32_e32 v59, vcc, 0, v59, vcc
	global_store_dwordx2 v[58:59], v[60:61], off offset:1536
	v_pk_mul_f32 v[58:59], v[68:69], v[56:57] op_sel_hi:[1,0]
	v_pk_mul_f32 v[60:61], v[70:71], v[56:57] op_sel_hi:[1,0]
	v_pk_mul_f32 v[58:59], v[24:25], v[58:59]
	v_pk_mul_f32 v[60:61], v[26:27], v[60:61]
	v_cvt_pk_bf16_f32 v58, v58, v59
	v_cvt_pk_bf16_f32 v59, v60, v61
	global_store_dwordx2 v[62:63], v[58:59], off offset:16
	v_pk_mul_f32 v[58:59], v[72:73], v[56:57] op_sel_hi:[1,0]
	v_pk_mul_f32 v[60:61], v[74:75], v[56:57] op_sel_hi:[1,0]
	v_pk_mul_f32 v[58:59], v[20:21], v[58:59]
	v_pk_mul_f32 v[60:61], v[22:23], v[60:61]
	v_cvt_pk_bf16_f32 v58, v58, v59
	v_cvt_pk_bf16_f32 v59, v60, v61
	global_store_dwordx2 v[62:63], v[58:59], off offset:32
	v_pk_mul_f32 v[58:59], v[76:77], v[56:57] op_sel_hi:[1,0]
	v_pk_mul_f32 v[60:61], v[78:79], v[56:57] op_sel_hi:[1,0]
	v_pk_mul_f32 v[58:59], v[16:17], v[58:59]
	v_pk_mul_f32 v[60:61], v[18:19], v[60:61]
	v_cvt_pk_bf16_f32 v58, v58, v59
	v_cvt_pk_bf16_f32 v59, v60, v61
	global_store_dwordx2 v[62:63], v[58:59], off offset:48
	v_pk_mul_f32 v[58:59], v[96:97], v[56:57] op_sel_hi:[1,0]
	v_pk_mul_f32 v[60:61], v[98:99], v[56:57] op_sel_hi:[1,0]
	v_pk_mul_f32 v[58:59], v[12:13], v[58:59]
	v_pk_mul_f32 v[60:61], v[14:15], v[60:61]
	v_cvt_pk_bf16_f32 v58, v58, v59
	v_cvt_pk_bf16_f32 v59, v60, v61
	global_store_dwordx2 v[62:63], v[58:59], off offset:64
	v_pk_mul_f32 v[58:59], v[100:101], v[56:57] op_sel_hi:[1,0]
	v_pk_mul_f32 v[60:61], v[102:103], v[56:57] op_sel_hi:[1,0]
	v_pk_mul_f32 v[58:59], v[8:9], v[58:59]
	v_pk_mul_f32 v[60:61], v[10:11], v[60:61]
	v_cvt_pk_bf16_f32 v58, v58, v59
	v_cvt_pk_bf16_f32 v59, v60, v61
	global_store_dwordx2 v[62:63], v[58:59], off offset:80
	v_pk_mul_f32 v[58:59], v[104:105], v[56:57] op_sel_hi:[1,0]
	v_pk_mul_f32 v[60:61], v[106:107], v[56:57] op_sel_hi:[1,0]
	v_pk_mul_f32 v[58:59], v[4:5], v[58:59]
	v_pk_mul_f32 v[60:61], v[6:7], v[60:61]
	v_cvt_pk_bf16_f32 v58, v58, v59
	v_cvt_pk_bf16_f32 v59, v60, v61
	global_store_dwordx2 v[62:63], v[58:59], off offset:96
	v_pk_mul_f32 v[58:59], v[108:109], v[56:57] op_sel_hi:[1,0]
	v_pk_mul_f32 v[56:57], v[110:111], v[56:57] op_sel_hi:[1,0]
	v_pk_mul_f32 v[58:59], v[0:1], v[58:59]
	v_pk_mul_f32 v[56:57], v[2:3], v[56:57]
	v_cvt_pk_bf16_f32 v58, v58, v59
	v_cvt_pk_bf16_f32 v59, v56, v57
	global_store_dwordx2 v[62:63], v[58:59], off offset:112
	v_lshl_add_u32 v58, v185, 2, s2
	ds_read2st64_b32 v[56:57], v58 offset1:1
	s_waitcnt lgkmcnt(0)
	v_add_f32_e32 v56, 0, v56
	v_add_f32_e32 v59, v56, v57
	ds_read2st64_b32 v[56:57], v58 offset0:2 offset1:3
	s_waitcnt lgkmcnt(0)
	v_add_f32_e32 v56, v59, v56
	v_add_f32_e32 v59, v56, v57
	ds_read2st64_b32 v[56:57], v58 offset0:4 offset1:5
	s_waitcnt lgkmcnt(0)
	v_add_f32_e32 v56, v59, v56
	v_add_f32_e32 v59, v56, v57
	ds_read2st64_b32 v[56:57], v58 offset0:6 offset1:7
	s_waitcnt lgkmcnt(0)
	v_add_f32_e32 v56, v59, v56
	v_add_f32_e32 v56, v56, v57
	v_fmamk_f32 v56, v56, 0x3b000000, v181
	v_cmp_gt_f32_e32 vcc, s13, v56
	v_mul_f32_e32 v57, 0x4f800000, v56
	s_nop 0
	v_cndmask_b32_e32 v56, v56, v57, vcc
	v_sqrt_f32_e32 v57, v56
	s_nop 0
	v_add_u32_e32 v58, -1, v57
	v_fma_f32 v59, -v58, v57, v56
	v_cmp_ge_f32_e64 s[42:43], 0, v59
	v_add_u32_e32 v59, 1, v57
	s_nop 0
	v_cndmask_b32_e64 v58, v57, v58, s[42:43]
	v_fma_f32 v57, -v59, v57, v56
	v_cmp_lt_f32_e64 s[42:43], 0, v57
	s_nop 1
	v_cndmask_b32_e64 v57, v58, v59, s[42:43]
	v_mul_f32_e32 v58, 0x37800000, v57
	v_cndmask_b32_e32 v57, v57, v58, vcc
	v_cmp_class_f32_e32 vcc, v56, v182
	s_nop 1
	v_cndmask_b32_e32 v56, v57, v56, vcc
	v_div_scale_f32 v57, s[2:3], v56, v56, 1.0
	v_rcp_f32_e32 v58, v57
	s_nop 0
	v_fma_f32 v59, -v57, v58, 1.0
	v_fmac_f32_e32 v58, v59, v58
	v_div_scale_f32 v59, vcc, 1.0, v56, 1.0
	v_mul_f32_e32 v60, v59, v58
	v_fma_f32 v61, -v57, v60, v59
	v_fmac_f32_e32 v60, v61, v58
	v_fma_f32 v57, -v57, v60, v59
	v_div_fmas_f32 v57, v57, v58, v60
	v_div_fixup_f32 v56, v57, v56, 1.0
	v_lshlrev_b64 v[58:59], 11, v[140:141]
	v_lshl_add_u64 v[58:59], s[54:55], 0, v[58:59]
	v_pk_mul_f32 v[60:61], v[80:81], v[56:57] op_sel_hi:[1,0]
	v_pk_mul_f32 v[44:45], v[44:45], v[56:57] op_sel_hi:[1,0]
	v_lshl_add_u64 v[58:59], v[58:59], 0, s[4:5]
	v_pk_mul_f32 v[28:29], v[28:29], v[60:61]
	v_pk_mul_f32 v[30:31], v[30:31], v[44:45]
	v_cvt_pk_bf16_f32 v28, v28, v29
	v_cvt_pk_bf16_f32 v29, v30, v31
	v_lshl_add_u64 v[30:31], v[58:59], 0, v[136:137]
	v_lshl_add_u64 v[44:45], v[30:31], 0, s[34:35]
	v_add_co_u32_e32 v30, vcc, s14, v30
	s_nop 1
	v_addc_co_u32_e32 v31, vcc, 0, v31, vcc
	global_store_dwordx2 v[30:31], v[28:29], off offset:1536
	v_pk_mul_f32 v[28:29], v[82:83], v[56:57] op_sel_hi:[1,0]
	s_nop 0
	v_pk_mul_f32 v[24:25], v[24:25], v[28:29]
	v_pk_mul_f32 v[28:29], v[46:47], v[56:57] op_sel_hi:[1,0]
	v_cvt_pk_bf16_f32 v24, v24, v25
	v_pk_mul_f32 v[26:27], v[26:27], v[28:29]
	s_nop 0
	v_cvt_pk_bf16_f32 v25, v26, v27
	global_store_dwordx2 v[44:45], v[24:25], off offset:16
	v_pk_mul_f32 v[24:25], v[84:85], v[56:57] op_sel_hi:[1,0]
	s_nop 0
	v_pk_mul_f32 v[20:21], v[20:21], v[24:25]
	v_pk_mul_f32 v[24:25], v[40:41], v[56:57] op_sel_hi:[1,0]
	v_cvt_pk_bf16_f32 v20, v20, v21
	v_pk_mul_f32 v[22:23], v[22:23], v[24:25]
	s_nop 0
	v_cvt_pk_bf16_f32 v21, v22, v23
	global_store_dwordx2 v[44:45], v[20:21], off offset:32
	v_pk_mul_f32 v[20:21], v[86:87], v[56:57] op_sel_hi:[1,0]
	s_nop 0
	v_pk_mul_f32 v[16:17], v[16:17], v[20:21]
	v_pk_mul_f32 v[20:21], v[42:43], v[56:57] op_sel_hi:[1,0]
	v_cvt_pk_bf16_f32 v16, v16, v17
	v_pk_mul_f32 v[18:19], v[18:19], v[20:21]
	s_nop 0
	v_cvt_pk_bf16_f32 v17, v18, v19
	global_store_dwordx2 v[44:45], v[16:17], off offset:48
	v_pk_mul_f32 v[16:17], v[48:49], v[56:57] op_sel_hi:[1,0]
	s_nop 0
	v_pk_mul_f32 v[12:13], v[12:13], v[16:17]
	v_pk_mul_f32 v[16:17], v[36:37], v[56:57] op_sel_hi:[1,0]
	v_cvt_pk_bf16_f32 v12, v12, v13
	v_pk_mul_f32 v[14:15], v[14:15], v[16:17]
	s_nop 0
	v_cvt_pk_bf16_f32 v13, v14, v15
	global_store_dwordx2 v[44:45], v[12:13], off offset:64
	v_pk_mul_f32 v[12:13], v[50:51], v[56:57] op_sel_hi:[1,0]
	s_nop 0
	v_pk_mul_f32 v[8:9], v[8:9], v[12:13]
	v_pk_mul_f32 v[12:13], v[38:39], v[56:57] op_sel_hi:[1,0]
	v_cvt_pk_bf16_f32 v8, v8, v9
	v_pk_mul_f32 v[10:11], v[10:11], v[12:13]
	s_nop 0
	v_cvt_pk_bf16_f32 v9, v10, v11
	global_store_dwordx2 v[44:45], v[8:9], off offset:80
	v_pk_mul_f32 v[8:9], v[52:53], v[56:57] op_sel_hi:[1,0]
	s_nop 0
	v_pk_mul_f32 v[4:5], v[4:5], v[8:9]
	v_pk_mul_f32 v[8:9], v[32:33], v[56:57] op_sel_hi:[1,0]
	v_cvt_pk_bf16_f32 v4, v4, v5
	v_pk_mul_f32 v[6:7], v[6:7], v[8:9]
	s_nop 0
	v_cvt_pk_bf16_f32 v5, v6, v7
	global_store_dwordx2 v[44:45], v[4:5], off offset:96
	v_pk_mul_f32 v[4:5], v[54:55], v[56:57] op_sel_hi:[1,0]
	s_nop 0
	v_pk_mul_f32 v[0:1], v[0:1], v[4:5]
	v_pk_mul_f32 v[4:5], v[34:35], v[56:57] op_sel_hi:[1,0]
	v_cvt_pk_bf16_f32 v0, v0, v1
	v_pk_mul_f32 v[2:3], v[2:3], v[4:5]
	s_nop 0
	v_cvt_pk_bf16_f32 v1, v2, v3
	global_store_dwordx2 v[44:45], v[0:1], off offset:112
	s_cbranch_scc0 .LBB0_1849
